# FFN1 down GEMM tile order: 4 row panels per XCD group instead of 2 (fewer distinct tile streams per XCD step)
# speedup vs baseline: 1.0044x; 1.0044x over previous
.LBB0_413:
	v_ashrrev_i32_e32 v2, 31, v0
	v_lshrrev_b32_e32 v2, 26, v2
	v_lshlrev_b32_e32 v1, 4, v0
	v_add_u32_e32 v2, v0, v2
	v_bfe_i32 v0, v0, 27, 1
	v_lshrrev_b32_e32 v0, 22, v0
	v_add_u32_e32 v0, v1, v0
	v_and_b32_e32 v0, 0xfffffc00, v0
	v_sub_u32_e32 v0, v1, v0
	v_lshrrev_b32_e32 v3, 4, v0
	v_bitop3_b32 v0, v3, v0, 32 bitop3:0x6c
	v_ashrrev_i32_e32 v4, 31, v0
	v_ashrrev_i32_e32 v2, 6, v2
	v_lshrrev_b32_e32 v4, 26, v4
	v_lshlrev_b32_e32 v3, 3, v2
	v_add_u32_e32 v4, v0, v4
	v_and_b32_e32 v3, -16, v3
	v_ashrrev_i32_e32 v5, 6, v4
	v_and_b32_e32 v4, 0xc0, v4
	v_add_u32_e32 v3, v5, v3
	v_sub_u32_e32 v0, v0, v4
	v_mov_b32_e32 v4, 1
	v_lshlrev_b32_e32 v2, 5, v2
	v_ashrrev_i16_sdwa v0, v4, sext(v0) dst_sel:DWORD dst_unused:UNUSED_PAD src0_sel:DWORD src1_sel:BYTE_0
	v_lshlrev_b32_e32 v6, 1, v3
	v_lshrrev_b32_e32 v7, 2, v3
	v_and_b32_e32 v5, 3, v5
	s_mov_b32 s1, 0x7ffe0
	v_and_b32_e32 v2, 32, v2
	v_bfe_i32 v0, v0, 0, 16
	v_and_b32_e32 v6, 24, v6
	v_and_b32_e32 v7, 4, v7
	v_and_or_b32 v5, v3, s1, v5
	v_or3_b32 v5, v5, v7, v6
	v_add_lshl_u32 v0, v2, v0, 1
	v_lshl_add_u32 v128, v3, 13, v0
	v_lshl_add_u32 v130, v5, 13, v0
	v_add_u32_e32 v0, 0x2000, v1
	v_ashrrev_i32_e32 v1, 31, v0
	v_lshrrev_b32_e32 v1, 22, v1
	v_add_u32_e32 v1, v0, v1
	v_ashrrev_i32_e32 v1, 10, v1
	v_mul_i32_i24_e32 v2, 0x400, v1
	v_sub_u32_e32 v0, v0, v2
	v_lshrrev_b32_e32 v2, 4, v0
	v_bitop3_b32 v0, v2, v0, 32 bitop3:0x6c
	s_ashr_i32 s0, s7, 3
	v_ashrrev_i32_e32 v3, 31, v0
	s_waitcnt lgkmcnt(0)
	s_add_u32 s25, s2, 0x2fa00000
	v_lshrrev_b32_e32 v3, 26, v3
	s_addc_u32 s26, s3, 0
	v_lshlrev_b32_e32 v2, 3, v1
	v_add_u32_e32 v3, v0, v3
	s_add_u32 s27, s2, 0xb400000
	v_and_b32_e32 v2, -16, v2
	v_ashrrev_i32_e32 v5, 6, v3
	s_addc_u32 s58, s3, 0
	v_add_u32_e32 v2, v5, v2
	v_and_b32_e32 v5, 3, v5
	s_add_i32 s0, s6, s0
	v_and_or_b32 v5, v2, s1, v5
	s_lshr_b32 s4, s0, 6
	s_lshl_b32 s5, s4, 2
	s_and_b32 s1, s0, 3
	s_add_i32 s42, s5, s1
	s_bfe_u32 s4, s0, 0x40002
	s_ashr_i32 s12, s13, 6
	s_ashr_i32 s43, s42, 31
	s_bfe_i64 s[6:7], s[4:5], 0x100000
	v_and_b32_e32 v3, 0xc0, v3
	s_ashr_i32 s16, s13, 8
	s_lshl_b32 s59, s12, 10
	s_lshl_b64 s[0:1], s[42:43], 21
	s_lshl_b64 s[6:7], s[6:7], 21
	v_sub_u32_e32 v0, v0, v3
	s_add_u32 s44, s27, s6
	v_lshlrev_b32_e32 v1, 5, v1
	v_ashrrev_i16_sdwa v0, v4, sext(v0) dst_sel:DWORD dst_unused:UNUSED_PAD src0_sel:DWORD src1_sel:BYTE_0
	v_lshlrev_b32_e32 v3, 1, v2
	v_lshrrev_b32_e32 v4, 2, v2
	s_addc_u32 s45, s58, s7
	s_add_i32 s43, s59, 0
	v_and_b32_e32 v1, 32, v1
	v_bfe_i32 v0, v0, 0, 16
	v_and_b32_e32 v3, 24, v3
	v_and_b32_e32 v4, 4, v4
	s_add_i32 m0, s43, 0x10000
	v_or3_b32 v3, v5, v4, v3
	v_add_lshl_u32 v0, v1, v0, 1
	global_load_lds_dwordx4 v130, s[44:45]
	s_add_i32 m0, s43, 0x12000
	v_lshl_add_u32 v134, v3, 13, v0
	s_add_u32 s6, s44, 0x100000
	global_load_lds_dwordx4 v134, s[44:45]
	s_addc_u32 s7, s45, 0
	s_add_i32 m0, s43, 0x14000
	v_lshl_add_u32 v132, v2, 13, v0
	global_load_lds_dwordx4 v130, s[6:7]
	s_add_i32 m0, s43, 0x16000
	s_add_u32 s46, s25, s0
	s_addc_u32 s47, s26, s1
	s_add_i32 s62, s43, 0x2000
	global_load_lds_dwordx4 v134, s[6:7]
	s_mov_b32 m0, s43
	s_add_u32 s0, s46, 0x100000
	global_load_lds_dwordx4 v128, s[46:47]
	s_mov_b32 m0, s62
	s_addc_u32 s1, s47, 0
	s_add_i32 s63, s43, 0x4000
	global_load_lds_dwordx4 v132, s[46:47]
	s_mov_b32 m0, s63
	s_add_i32 s64, s43, 0x6000
	global_load_lds_dwordx4 v128, s[0:1]
	s_mov_b32 m0, s64
	v_mov_b32_e32 v131, 0
	global_load_lds_dwordx4 v132, s[0:1]
	v_mov_b32_e32 v135, v131
	v_mov_b32_e32 v129, v131
	v_mov_b32_e32 v133, v131
	s_cmp_eq_u32 s16, 1
	s_mov_b32 s5, 0
	v_lshl_add_u64 v[6:7], s[44:45], 0, v[130:131]
	v_lshl_add_u64 v[2:3], s[44:45], 0, v[134:135]
	s_mov_b64 s[6:7], 0x100000
	v_lshl_add_u64 v[0:1], s[46:47], 0, v[128:129]
	s_cselect_b64 s[8:9], -1, 0
	s_cmp_lg_u32 s16, 1
	v_lshl_add_u64 v[4:5], s[46:47], 0, v[132:133]
	s_cbranch_scc1 .LBB0_415
	s_barrier

.LBB0_423:
	s_ashr_i32 s0, s4, 3
	s_add_i32 s0, s36, s0
	s_ashr_i32 s1, s0, 31
	s_lshr_b32 s1, s1, 26
	s_add_i32 s1, s0, s1
	s_ashr_i32 s4, s1, 6
	s_lshl_b32 s4, s4, 2
	s_sub_i32 s13, 64, s4
	s_min_i32 s13, s13, 4
	s_abs_i32 s34, s13
	v_cvt_f32_u32_e32 v0, s34
	s_sub_i32 s36, 0, s34
	s_andn2_b32 s1, s1, 63
	s_sub_i32 s0, s0, s1
	v_rcp_iflag_f32_e32 v0, v0
	s_abs_i32 s1, s0
	s_xor_b32 s35, s0, s13
	s_ashr_i32 s35, s35, 31
	v_mul_f32_e32 v0, 0x4f7ffffe, v0
	v_cvt_u32_f32_e32 v0, v0
	s_nop 0
	v_readfirstlane_b32 s37, v0
	s_mul_i32 s36, s36, s37
	s_mul_hi_u32 s36, s37, s36
	s_add_i32 s37, s37, s36
	s_mul_hi_u32 s36, s1, s37
	s_mul_i32 s37, s36, s34
	s_sub_i32 s1, s1, s37
	s_add_i32 s38, s36, 1
	s_sub_i32 s37, s1, s34
	s_cmp_ge_u32 s1, s34
	s_cselect_b32 s36, s38, s36
	s_cselect_b32 s1, s37, s1
	s_add_i32 s37, s36, 1
	s_cmp_ge_u32 s1, s34
	s_cselect_b32 s1, s37, s36
	s_xor_b32 s1, s1, s35
	s_sub_i32 s34, s1, s35
	s_mul_i32 s1, s34, s13
	s_sub_i32 s0, s0, s1
	s_add_i32 s36, s4, s0
